# v19 + DF hot-loop address arithmetic folded into immediates / SGPR bases
# speedup vs baseline: 1.0045x; 1.0045x over previous
.LBB0_553:
	s_or_b32 s4, s63, s60
	v_mov_b32_e32 v233, v225
	s_bitcmp0_b32 s63, 0
	s_cselect_b32 s70, s59, s61
	v_readfirstlane_b32 s68, v233
	s_bfe_u32 s65, s68, 0x20006
	s_lshl_b32 s71, s70, 7
	s_lshl_b32 s67, s65, 5
	v_and_b32_e32 v231, 31, v233
	s_or_b32 s69, s67, s71
	s_add_i32 s40, s4, s62
	v_or_b32_e32 v212, s69, v231
	s_ashr_i32 s41, s40, 31
	s_ashr_i32 s66, s68, 8
	s_lshl_b64 s[42:43], s[40:41], 19
	v_lshl_add_u64 v[0:1], s[38:39], 0, v[212:213]
	s_add_u32 s72, s14, s42
	v_mad_u64_u32 v[2:3], s[40:41], v0, s44, v[214:215]
	s_addc_u32 s73, s15, s43
	v_mad_i32_i24 v3, v1, s44, v3
	s_lshl_b32 s64, s4, 7
	s_lshl_b32 s4, s4, 8
	s_lshl_b32 s40, s66, 6
	v_bfe_u32 v4, v233, 5, 1
	v_lshl_add_u64 v[0:1], v[2:3], 0, s[4:5]
	s_ashr_i32 s41, s40, 31
	v_lshl_add_u64 v[0:1], s[40:41], 1, v[0:1]
	v_lshlrev_b32_e32 v216, 4, v4
	v_mov_b32_e32 v217, v213
	v_lshl_add_u64 v[0:1], v[0:1], 0, v[216:217]
	v_lshl_add_u64 v[2:3], v[0:1], 0, s[6:7]
	v_add_co_u32_e32 v0, vcc, s45, v0
	s_add_u32 s42, s81, s42
	s_nop 0
	v_addc_co_u32_e32 v1, vcc, 0, v1, vcc
	global_load_dwordx4 v[128:131], v[2:3], off offset:32
	global_load_dwordx4 v[132:135], v[2:3], off offset:64
	global_load_dwordx4 v[136:139], v[0:1], off offset:2048
	global_load_dwordx4 v[140:143], v[2:3], off offset:96
	v_lshlrev_b32_e32 v0, 3, v233
	s_addc_u32 s43, s82, s43
	v_ashrrev_i32_e32 v1, 31, v0
	s_lshl_b32 s41, s70, 1
	v_lshlrev_b64 v[0:1], 1, v[0:1]
	v_mov_b32_e32 v246, v0
	v_add_u32_e32 v245, 0x2000, v0
	s_or_b32 s70, s41, 1
	s_mov_b64 s[88:89], s[72:73]
	v_lshl_add_u64 v[218:219], s[72:73], 0, v[0:1]
	s_lshl_b32 s4, s70, 14
	s_mov_b64 s[90:91], s[42:43]
	v_lshl_add_u64 v[220:221], s[42:43], 0, v[0:1]
	v_lshl_add_u64 v[0:1], v[218:219], 0, s[4:5]
	s_barrier
	v_lshl_add_u64 v[2:3], v[220:221], 0, s[4:5]
	global_load_dwordx4 v[144:147], v[0:1], off
	global_load_dwordx4 v[148:151], v[2:3], off
	v_add_co_u32_e32 v0, vcc, s47, v0
	v_lshlrev_b32_e32 v217, 3, v4
	s_nop 0
	v_addc_co_u32_e32 v1, vcc, 0, v1, vcc
	v_add_co_u32_e32 v2, vcc, s47, v2
	v_mul_u32_u24_e32 v230, 0x110, v231
	s_nop 0
	v_addc_co_u32_e32 v3, vcc, 0, v3, vcc
	global_load_dwordx4 v[152:155], v[0:1], off
	global_load_dwordx4 v[156:159], v[2:3], off
	v_lshrrev_b32_e32 v0, 4, v233
	v_lshlrev_b32_e32 v2, 4, v233
	v_mov_b32_e32 v1, 0x14e60
	v_lshrrev_b32_e32 v3, 3, v233
	v_mul_lo_u32 v5, v0, s46
	v_and_b32_e32 v0, 0x70, v2
	v_and_b32_e32 v6, 0xf0, v2
	v_mad_u64_u32 v[222:223], s[42:43], v3, s48, v[0:1]
	v_add3_u32 v234, 0, v5, v6
	v_add_u32_e32 v0, 0, v222
	v_or_b32_e32 v2, s40, v217
	v_lshlrev_b32_e32 v2, 1, v2
	v_mov_b32_e32 v48, v213
	v_mov_b32_e32 v49, v213
	v_mov_b32_e32 v62, v213
	v_mov_b32_e32 v63, v213
	v_lshlrev_b32_e32 v232, 2, v4
	v_add3_u32 v235, 0, v230, v2
	v_mad_u32_u24 v236, v231, s48, v1
	v_mov_b32_e32 v50, v213
	v_mov_b32_e32 v51, v213
	v_mov_b32_e32 v52, v213
	v_mov_b32_e32 v53, v213
	v_mov_b32_e32 v54, v213
	v_mov_b32_e32 v55, v213
	v_mov_b32_e32 v56, v213
	v_mov_b32_e32 v57, v213
	v_mov_b32_e32 v58, v213
	v_mov_b32_e32 v59, v213
	v_mov_b32_e32 v60, v213
	v_mov_b32_e32 v61, v213
	v_mov_b64_e32 v[32:33], v[48:49]
	v_mov_b64_e32 v[16:17], v[48:49]
	s_waitcnt vmcnt(8)
	v_mov_b64_e32 v[78:79], v[62:63]
	s_mov_b32 s72, 1
	s_waitcnt vmcnt(3)
	ds_write_b128 v234, v[144:147]
	s_waitcnt vmcnt(2)
	ds_write_b128 v0, v[148:151] offset:34816
	s_waitcnt vmcnt(1)
	ds_write_b128 v234, v[152:155] offset:8704
	s_waitcnt vmcnt(0)
	ds_write_b128 v0, v[156:159] offset:44032
	v_mov_b32_e32 v0, 0x14e40
	v_mad_u32_u24 v237, v231, s48, v0
	v_mov_b32_e32 v0, 0x14e20
	v_mad_u32_u24 v238, v231, s48, v0
	v_mov_b32_e32 v0, 0x14e00
	v_mad_u32_u24 v239, v231, s48, v0
	v_mov_b32_e32 v0, 0x13c00
	v_mad_u32_u24 v240, v231, s48, v0
	v_mov_b32_e32 v0, 0x12a60
	v_mad_u32_u24 v241, v231, s48, v0
	v_mov_b32_e32 v0, 0x12a40
	v_mad_u32_u24 v242, v231, s48, v0
	v_mov_b32_e32 v0, 0x12a20
	v_mad_u32_u24 v243, v231, s48, v0
	v_mov_b32_e32 v0, 0x12a00
	v_mad_u32_u24 v244, v231, s48, v0
	v_mov_b32_e32 v0, 0x11800
	v_mad_u32_u24 v248, v231, s48, v0
	v_add_u32_e32 v248, v248, v216
	v_mov_b64_e32 v[0:1], v[48:49]
	s_mov_b32 s73, 0
	s_mov_b32 s74, 2
	s_or_b32 s75, s69, 31
	s_mov_b64 s[42:43], 0
	v_mov_b32_e32 v224, 1.0
	v_mov_b32_e32 v249, 0xf149f2ca
	v_mov_b32_e32 v223, 0
	s_mov_b32 s4, s41
	v_mov_b64_e32 v[34:35], v[50:51]
	v_mov_b64_e32 v[36:37], v[52:53]
	v_mov_b64_e32 v[38:39], v[54:55]
	v_mov_b64_e32 v[40:41], v[56:57]
	v_mov_b64_e32 v[42:43], v[58:59]
	v_mov_b64_e32 v[44:45], v[60:61]
	v_mov_b64_e32 v[46:47], v[62:63]
	v_mov_b64_e32 v[18:19], v[50:51]
	v_mov_b64_e32 v[20:21], v[52:53]
	v_mov_b64_e32 v[22:23], v[54:55]
	v_mov_b64_e32 v[24:25], v[56:57]
	v_mov_b64_e32 v[26:27], v[58:59]
	v_mov_b64_e32 v[28:29], v[60:61]
	v_mov_b64_e32 v[30:31], v[62:63]
	v_mov_b64_e32 v[2:3], v[50:51]
	v_mov_b64_e32 v[4:5], v[52:53]
	v_mov_b64_e32 v[6:7], v[54:55]
	v_mov_b64_e32 v[8:9], v[56:57]
	v_mov_b64_e32 v[10:11], v[58:59]
	v_mov_b64_e32 v[12:13], v[60:61]
	v_mov_b64_e32 v[14:15], v[62:63]
	v_mov_b64_e32 v[76:77], v[60:61]
	v_mov_b64_e32 v[74:75], v[58:59]
	v_mov_b64_e32 v[72:73], v[56:57]
	v_mov_b64_e32 v[70:71], v[54:55]
	v_mov_b64_e32 v[68:69], v[52:53]
	v_mov_b64_e32 v[66:67], v[50:51]
	v_mov_b64_e32 v[64:65], v[48:49]
	s_waitcnt lgkmcnt(0)
	s_barrier
	s_branch .LBB0_555

.LBB0_555:
	s_add_i32 s76, s4, 1
	s_cmp_gt_i32 s76, 0
	s_cselect_b64 s[40:41], -1, 0
	s_cmp_lt_i32 s76, 1
	s_cbranch_scc1 .LBB0_557
	s_lshl_b64 s[76:77], s[4:5], 14
	s_add_u32 s92, s88, s76
	s_addc_u32 s93, s89, s77
	s_add_u32 s94, s90, s76
	s_addc_u32 s95, s91, s77
	global_load_dwordx4 v[144:147], v246, s[92:93]
	global_load_dwordx4 v[148:151], v246, s[94:95]
	global_load_dwordx4 v[152:155], v245, s[92:93]
	global_load_dwordx4 v[156:159], v245, s[94:95]
.LBB0_557:
	s_add_i32 s76, s71, 64
	s_cmp_gt_i32 s76, s75
	s_cbranch_scc1 .LBB0_568
	s_mul_hi_u32 s76, s74, 0xaaaaaaab
	s_lshr_b32 s76, s76, 1
	s_bitcmp1_b32 s72, 0
	s_cselect_b32 s77, 0, 0x4400
	v_add_u32_e32 v96, s77, v235
	ds_read_b128 v[92:95], v96
	ds_read_b128 v[88:91], v96 offset:32
	ds_read_b128 v[84:87], v96 offset:64
	ds_read_b128 v[80:83], v96 offset:96
	ds_read_b128 v[120:123], v96 offset:8704
	ds_read_b128 v[116:119], v96 offset:8736
	ds_read_b128 v[112:115], v96 offset:8768
	ds_read_b128 v[208:211], v96 offset:8800
	s_mul_i32 s76, s76, 0xd800
	s_sub_i32 s86, s73, s76
	s_andn2_b64 vcc, exec, s[42:43]
	v_add_u32_e32 v247, s86, v248
	s_cbranch_vccnz .LBB0_560
	ds_read_b128 v[184:187], v247 offset:32
	ds_read_b128 v[180:183], v247 offset:64
	ds_read_b128 v[188:191], v247
	ds_read_b128 v[176:179], v247 offset:96

.LBB0_565:
	ds_read_b128 v[124:127], v247 offset:4608
	ds_read_b128 v[120:123], v247 offset:4640
	ds_read_b128 v[116:119], v247 offset:4672
	ds_read_b128 v[112:115], v247 offset:4704
	v_mfma_f32_32x32x16_bf16 v[48:63], v[188:191], v[172:175], v[48:63]
	v_max3_f32 v192, v96, s49, v97
	v_max3_f32 v192, v192, v98, v99
	v_max3_f32 v192, v192, v100, v101
	v_max3_f32 v192, v192, v102, v103
	v_mfma_f32_32x32x16_bf16 v[48:63], v[184:187], v[168:171], v[48:63]
	v_max3_f32 v188, v192, v104, v105
	v_max3_f32 v188, v188, v106, v107
	v_max3_f32 v188, v188, v108, v109
	v_max3_f32 v188, v188, v110, v111
	v_mfma_f32_32x32x16_bf16 v[48:63], v[180:183], v[164:167], v[48:63]
	v_max3_f32 v184, v188, v80, v81
	v_max3_f32 v184, v184, v82, v83
	v_max3_f32 v184, v184, v84, v85
	v_max3_f32 v184, v184, v86, v87
	v_max3_f32 v180, v184, v88, v89
	v_max3_f32 v180, v180, v90, v91
	v_max3_f32 v180, v180, v92, v93
	v_mfma_f32_32x32x16_bf16 v[48:63], v[176:179], v[160:163], v[48:63]
	v_max3_f32 v180, v180, v94, v95
	v_mov_b32_e32 v181, v180
	s_nop 1
	v_permlane32_swap_b32_e32 v180, v181
	v_max_f32_e32 v176, v181, v181
	v_max_f32_e32 v177, v180, v180
	v_max_f32_e32 v176, v177, v176
	v_cmp_ge_f32_e32 vcc, s50, v176
	s_cmp_eq_u64 vcc, exec
	v_mov_b32_e32 v224, 1.0
	s_cbranch_scc1 .LBB0_567
	v_max_f32_e32 v64, v176, v176
	v_max_f32_e32 v65, 0, v64
	v_exp_f32_e64 v224, -v65
	v_add_f32_e32 v249, v249, v65
	v_xor_b32_e32 v64, 0x80000000, v249
	v_sub_f32_e32 v96, v96, v65
	v_sub_f32_e32 v97, v97, v65
	v_sub_f32_e32 v98, v98, v65
	v_sub_f32_e32 v99, v99, v65
	v_sub_f32_e32 v100, v100, v65
	v_sub_f32_e32 v101, v101, v65
	v_sub_f32_e32 v102, v102, v65
	v_sub_f32_e32 v103, v103, v65
	v_sub_f32_e32 v104, v104, v65
	v_sub_f32_e32 v105, v105, v65
	v_sub_f32_e32 v106, v106, v65
	v_sub_f32_e32 v107, v107, v65
	v_sub_f32_e32 v108, v108, v65
	v_sub_f32_e32 v109, v109, v65
	v_sub_f32_e32 v110, v110, v65
	v_sub_f32_e32 v111, v111, v65
	v_sub_f32_e32 v80, v80, v65
	v_sub_f32_e32 v81, v81, v65
	v_sub_f32_e32 v82, v82, v65
	v_sub_f32_e32 v83, v83, v65
	v_sub_f32_e32 v84, v84, v65
	v_sub_f32_e32 v85, v85, v65
	v_sub_f32_e32 v86, v86, v65
	v_sub_f32_e32 v87, v87, v65
	v_sub_f32_e32 v88, v88, v65
	v_sub_f32_e32 v89, v89, v65
	v_sub_f32_e32 v90, v90, v65
	v_sub_f32_e32 v91, v91, v65
	v_sub_f32_e32 v92, v92, v65
	v_sub_f32_e32 v93, v93, v65
	v_sub_f32_e32 v94, v94, v65
	v_sub_f32_e32 v95, v95, v65
	v_mov_b32_e32 v65, v64
	v_mov_b32_e32 v66, v64
	v_mov_b32_e32 v67, v64
	v_mov_b32_e32 v68, v64
	v_mov_b32_e32 v69, v64
	v_mov_b32_e32 v70, v64
	v_mov_b32_e32 v71, v64
	v_mov_b32_e32 v72, v64
	v_mov_b32_e32 v73, v64
	v_mov_b32_e32 v74, v64
	v_mov_b32_e32 v75, v64
	v_mov_b32_e32 v76, v64
	v_mov_b32_e32 v77, v64
	v_mov_b32_e32 v78, v64
	v_mov_b32_e32 v79, v64
.LBB0_567:
	s_waitcnt lgkmcnt(3)
	v_mfma_f32_32x32x16_bf16 v[32:47], v[124:127], v[172:175], v[32:47]
	ds_read_b128 v[188:191], v247 offset:9216
	ds_read_b128 v[184:187], v247 offset:9248
	ds_read_b128 v[180:183], v247 offset:9280
	ds_read_b128 v[176:179], v247 offset:9312
	v_exp_f32_e32 v200, v96
	v_exp_f32_e32 v201, v97
	v_exp_f32_e32 v202, v98
	v_exp_f32_e32 v203, v99
	v_cvt_pk_bf16_f32 v192, v200, v201
	v_cvt_pk_bf16_f32 v193, v202, v203
	s_waitcnt lgkmcnt(6)
	v_mfma_f32_32x32x16_bf16 v[32:47], v[120:123], v[168:171], v[32:47]
	v_exp_f32_e32 v124, v100
	v_exp_f32_e32 v125, v101
	v_exp_f32_e32 v126, v102
	v_exp_f32_e32 v127, v103
	v_cvt_pk_bf16_f32 v194, v124, v125
	v_cvt_pk_bf16_f32 v195, v126, v127
	s_waitcnt lgkmcnt(5)
	v_mfma_f32_32x32x16_bf16 v[32:47], v[116:119], v[164:167], v[32:47]
	v_exp_f32_e32 v120, v104
	v_exp_f32_e32 v121, v105
	v_exp_f32_e32 v122, v106
	v_exp_f32_e32 v123, v107
	v_cvt_pk_bf16_f32 v196, v120, v121
	v_cvt_pk_bf16_f32 v197, v122, v123
	s_waitcnt lgkmcnt(4)
	v_mfma_f32_32x32x16_bf16 v[32:47], v[112:115], v[160:163], v[32:47]
	v_exp_f32_e32 v116, v108
	v_exp_f32_e32 v117, v109
	v_exp_f32_e32 v118, v110
	v_exp_f32_e32 v119, v111
	v_cvt_pk_bf16_f32 v198, v116, v117
	v_cvt_pk_bf16_f32 v199, v118, v119
	v_pk_add_f32 v[112:113], v[200:201], 0 op_sel_hi:[1,0]
	s_waitcnt lgkmcnt(3)
	v_mfma_f32_32x32x16_bf16 v[16:31], v[188:191], v[172:175], v[16:31]
	v_add_f32_e64 v112, v202, v112
	v_add_f32_e64 v113, v203, v113
	v_pk_add_f32 v[112:113], v[124:125], v[112:113]
	ds_read_b128 v[96:99], v247 offset:13824
	ds_read_b128 v[100:103], v247 offset:13856
	ds_read_b128 v[104:107], v247 offset:13888
	ds_read_b128 v[108:111], v247 offset:13920
	v_pk_add_f32 v[112:113], v[126:127], v[112:113]
	v_exp_f32_e32 v80, v80
	v_exp_f32_e32 v81, v81
	v_pk_add_f32 v[112:113], v[120:121], v[112:113]
	v_cvt_pk_bf16_f32 v200, v80, v81
	v_pk_add_f32 v[112:113], v[122:123], v[112:113]
	s_nop 0
	v_pk_add_f32 v[112:113], v[116:117], v[112:113]
	s_nop 0
	v_pk_add_f32 v[112:113], v[118:119], v[112:113]
	s_nop 0
	v_pk_add_f32 v[112:113], v[80:81], v[112:113]
	s_waitcnt lgkmcnt(6)
	v_mfma_f32_32x32x16_bf16 v[16:31], v[184:187], v[168:171], v[16:31]
	v_exp_f32_e32 v80, v82
	v_exp_f32_e32 v81, v83
	s_nop 0
	v_cvt_pk_bf16_f32 v201, v80, v81
	v_pk_add_f32 v[82:83], v[80:81], v[112:113]
	s_waitcnt lgkmcnt(5)
	v_mfma_f32_32x32x16_bf16 v[16:31], v[180:183], v[164:167], v[16:31]
	v_exp_f32_e32 v80, v84
	v_exp_f32_e32 v81, v85
	s_nop 0
	v_cvt_pk_bf16_f32 v202, v80, v81
	v_pk_add_f32 v[82:83], v[80:81], v[82:83]
	s_waitcnt lgkmcnt(4)
	v_mfma_f32_32x32x16_bf16 v[16:31], v[176:179], v[160:163], v[16:31]
	v_exp_f32_e32 v80, v86
	v_exp_f32_e32 v81, v87
	s_nop 0
	v_cvt_pk_bf16_f32 v203, v80, v81
	v_pk_add_f32 v[82:83], v[80:81], v[82:83]
	s_waitcnt lgkmcnt(3)
	v_mfma_f32_32x32x16_bf16 v[0:15], v[96:99], v[172:175], v[0:15]
	v_exp_f32_e32 v80, v88
	v_exp_f32_e32 v81, v89
	s_nop 0
	v_cvt_pk_bf16_f32 v204, v80, v81
	v_pk_add_f32 v[82:83], v[80:81], v[82:83]
	s_waitcnt lgkmcnt(2)
	v_mfma_f32_32x32x16_bf16 v[0:15], v[100:103], v[168:171], v[0:15]
	v_exp_f32_e32 v80, v90
	v_exp_f32_e32 v81, v91
	s_nop 0
	v_cvt_pk_bf16_f32 v205, v80, v81
	v_pk_add_f32 v[82:83], v[80:81], v[82:83]
	s_waitcnt lgkmcnt(1)
	v_mfma_f32_32x32x16_bf16 v[0:15], v[104:107], v[164:167], v[0:15]
	v_exp_f32_e32 v80, v92
	v_exp_f32_e32 v81, v93
	s_nop 0
	v_cvt_pk_bf16_f32 v206, v80, v81
	v_pk_add_f32 v[82:83], v[80:81], v[82:83]
	s_waitcnt lgkmcnt(0)
	v_mfma_f32_32x32x16_bf16 v[0:15], v[108:111], v[160:163], v[0:15]
	v_exp_f32_e32 v80, v94
	v_exp_f32_e32 v81, v95
	s_nop 0
	v_cvt_pk_bf16_f32 v207, v80, v81
	v_pk_add_f32 v[82:83], v[80:81], v[82:83]
	s_nop 0
	v_add_f32_e32 v252, v82, v83
	v_fmac_f32_e32 v252, v223, v224
	v_mov_b32_e32 v163, v207
	v_mov_b32_e32 v162, v206
	v_mov_b32_e32 v161, v205
	v_mov_b32_e32 v160, v204
	v_mov_b32_e32 v167, v203
	v_mov_b32_e32 v166, v202
	v_mov_b32_e32 v165, v201
	v_mov_b32_e32 v164, v200
	v_mov_b32_e32 v171, v199
	v_mov_b32_e32 v170, v198
	v_mov_b32_e32 v169, v197
	v_mov_b32_e32 v168, v196
	v_mov_b32_e32 v175, v195
	v_mov_b32_e32 v174, v194
	v_mov_b32_e32 v173, v193
	v_mov_b32_e32 v172, v192
	s_branch .LBB0_570
